# wave_sum in the row passes and prologue rmsnorm: six ds_bpermute round trips replaced by DPP row adds + v_permlane16/32_swap adds
# baseline (speedup 1.0000x reference)
.LBB0_19:
	global_load_dwordx4 v[14:17], v[4:5], off offset:-3072 nt
	global_load_dwordx4 v[18:21], v[4:5], off offset:-2048 nt
	global_load_dwordx4 v[22:25], v[4:5], off offset:-1024 nt
	global_load_dwordx4 v[26:29], v[4:5], off nt
	s_add_i32 s11, s11, s4
	v_lshl_add_u64 v[4:5], v[4:5], 0, s[12:13]
	s_cmpk_gt_i32 s11, 0x7ff
	s_waitcnt vmcnt(3)
	v_mul_f32_e32 v30, v15, v15
	v_mul_f32_e32 v31, v17, v17
	s_waitcnt vmcnt(2)
	v_mul_f32_e32 v32, v19, v19
	v_mul_f32_e32 v33, v21, v21
	s_waitcnt vmcnt(1)
	v_mul_f32_e32 v34, v23, v23
	v_mul_f32_e32 v35, v25, v25
	v_fmac_f32_e32 v30, v14, v14
	v_fmac_f32_e32 v31, v16, v16
	v_fmac_f32_e32 v32, v18, v18
	v_fmac_f32_e32 v33, v20, v20
	s_waitcnt vmcnt(0)
	v_mul_f32_e32 v36, v27, v27
	v_mul_f32_e32 v37, v29, v29
	v_fmac_f32_e32 v34, v22, v22
	v_fmac_f32_e32 v35, v24, v24
	v_add_f32_e32 v30, v30, v31
	v_add_f32_e32 v31, v32, v33
	v_fmac_f32_e32 v36, v26, v26
	v_fmac_f32_e32 v37, v28, v28
	v_add_f32_e32 v32, v34, v35
	v_add_f32_e32 v30, v30, v31
	v_add_f32_e32 v33, v36, v37
	v_add_f32_e32 v30, v30, v32
	v_add_f32_e32 v30, v30, v33
	s_nop 1
	v_add_f32_dpp v30, v30, v30 quad_perm:[1,0,3,2] row_mask:0xf bank_mask:0xf
	s_nop 1
	v_add_f32_dpp v30, v30, v30 quad_perm:[2,3,0,1] row_mask:0xf bank_mask:0xf
	s_nop 1
	v_add_f32_dpp v30, v30, v30 row_half_mirror row_mask:0xf bank_mask:0xf
	s_nop 1
	v_add_f32_dpp v30, v30, v30 row_mirror row_mask:0xf bank_mask:0xf
	v_mov_b32_e32 v31, v30
	s_nop 1
	v_permlane16_swap_b32_e32 v31, v30
	v_add_f32_e32 v30, v30, v31
	v_mov_b32_e32 v31, v30
	s_nop 1
	v_permlane32_swap_b32_e32 v31, v30
	v_add_f32_e32 v30, v30, v31
	s_waitcnt lgkmcnt(0)
	s_waitcnt lgkmcnt(0)
	s_waitcnt lgkmcnt(0)
	s_waitcnt lgkmcnt(0)
	s_waitcnt lgkmcnt(0)
	s_waitcnt lgkmcnt(0)
	v_fmamk_f32 v30, v30, 0x3a800000, v12
	v_mul_f32_e32 v31, 0x4f800000, v30
	v_cmp_gt_f32_e32 vcc, s5, v30
	s_nop 1
	v_cndmask_b32_e32 v30, v30, v31, vcc
	v_sqrt_f32_e32 v31, v30
	s_nop 0
	v_add_u32_e32 v32, -1, v31
	v_add_u32_e32 v33, 1, v31
	v_fma_f32 v34, -v32, v31, v30
	v_fma_f32 v35, -v33, v31, v30
	v_cmp_ge_f32_e64 s[0:1], 0, v34
	s_nop 1
	v_cndmask_b32_e64 v31, v31, v32, s[0:1]
	v_cmp_lt_f32_e64 s[0:1], 0, v35
	s_nop 1
	v_cndmask_b32_e64 v31, v31, v33, s[0:1]
	v_mul_f32_e32 v32, 0x37800000, v31
	v_cndmask_b32_e32 v31, v31, v32, vcc
	v_cmp_class_f32_e32 vcc, v30, v13
	s_nop 1
	v_cndmask_b32_e32 v30, v31, v30, vcc
	v_div_scale_f32 v31, s[0:1], v30, v30, 1.0
	v_rcp_f32_e32 v33, v31
	v_div_scale_f32 v32, vcc, 1.0, v30, 1.0
	v_fma_f32 v34, -v31, v33, 1.0
	v_fmac_f32_e32 v33, v34, v33
	v_mul_f32_e32 v34, v32, v33
	v_fma_f32 v35, -v31, v34, v32
	v_fmac_f32_e32 v34, v35, v33
	v_fma_f32 v31, -v31, v34, v32
	v_div_fmas_f32 v31, v31, v33, v34
	v_div_fixup_f32 v30, v31, v30, 1.0
	v_mul_f32_e32 v14, v14, v30
	v_mul_f32_e32 v16, v16, v30
	v_mul_f32_e32 v15, v15, v30
	v_mul_f32_e32 v17, v17, v30
	v_mul_f32_e32 v18, v18, v30
	v_mul_f32_e32 v19, v19, v30
	v_mul_f32_e32 v20, v20, v30
	v_mul_f32_e32 v21, v21, v30
	v_mul_f32_e32 v22, v22, v30
	v_mul_f32_e32 v23, v23, v30
	v_mul_f32_e32 v24, v24, v30
	v_mul_f32_e32 v25, v25, v30
	v_mul_f32_e32 v26, v26, v30
	v_mul_f32_e32 v27, v27, v30
	v_mul_f32_e32 v28, v28, v30
	v_mul_f32_e32 v29, v29, v30
	v_bfe_u32 v30, v14, 16, 1
	v_bfe_u32 v32, v16, 16, 1
	v_bfe_u32 v31, v15, 16, 1
	v_bfe_u32 v33, v17, 16, 1
	v_bfe_u32 v34, v18, 16, 1
	v_bfe_u32 v36, v20, 16, 1
	v_bfe_u32 v38, v22, 16, 1
	v_bfe_u32 v40, v24, 16, 1
	v_bfe_u32 v42, v26, 16, 1
	v_bfe_u32 v44, v28, 16, 1
	v_add3_u32 v14, v14, v30, s6
	v_add3_u32 v16, v16, v32, s6
	v_bfe_u32 v35, v19, 16, 1
	v_bfe_u32 v37, v21, 16, 1
	v_bfe_u32 v39, v23, 16, 1
	v_bfe_u32 v41, v25, 16, 1
	v_bfe_u32 v43, v27, 16, 1
	v_bfe_u32 v45, v29, 16, 1
	v_add3_u32 v15, v15, v31, s6
	v_add3_u32 v17, v17, v33, s6
	v_add3_u32 v18, v18, v34, s6
	v_add3_u32 v20, v20, v36, s6
	v_add3_u32 v22, v22, v38, s6
	v_add3_u32 v24, v24, v40, s6
	v_add3_u32 v26, v26, v42, s6
	v_add3_u32 v28, v28, v44, s6
	v_lshrrev_b32_e32 v14, 16, v14
	v_lshrrev_b32_e32 v16, 16, v16
	v_add3_u32 v19, v19, v35, s6
	v_add3_u32 v21, v21, v37, s6
	v_add3_u32 v23, v23, v39, s6
	v_add3_u32 v25, v25, v41, s6
	v_add3_u32 v27, v27, v43, s6
	v_add3_u32 v29, v29, v45, s6
	v_lshrrev_b32_e32 v18, 16, v18
	v_lshrrev_b32_e32 v20, 16, v20
	v_lshrrev_b32_e32 v22, 16, v22
	v_lshrrev_b32_e32 v24, 16, v24
	v_lshrrev_b32_e32 v26, 16, v26
	v_lshrrev_b32_e32 v28, 16, v28
	v_and_or_b32 v14, v15, s7, v14
	v_and_or_b32 v15, v17, s7, v16
	v_and_or_b32 v16, v19, s7, v18
	v_and_or_b32 v17, v21, s7, v20
	v_and_or_b32 v18, v23, s7, v22
	v_and_or_b32 v19, v25, s7, v24
	v_and_or_b32 v20, v27, s7, v26
	v_and_or_b32 v21, v29, s7, v28
	global_store_dwordx2 v[2:3], v[14:15], off
	global_store_dwordx2 v[2:3], v[16:17], off offset:512
	global_store_dwordx2 v[2:3], v[18:19], off offset:1024
	global_store_dwordx2 v[2:3], v[20:21], off offset:1536
	v_lshl_add_u64 v[2:3], v[2:3], 0, s[2:3]
	s_cbranch_scc0 .LBB0_19

.Lxr_skip:
	v_mul_f32_e32 v31, v15, v15
	v_mul_f32_e32 v32, v17, v17
	v_mul_f32_e32 v33, v11, v11
	v_mul_f32_e32 v34, v13, v13
	v_mul_f32_e32 v35, v7, v7
	v_mul_f32_e32 v36, v9, v9
	v_fmac_f32_e32 v31, v14, v14
	v_fmac_f32_e32 v32, v16, v16
	v_fmac_f32_e32 v33, v10, v10
	v_fmac_f32_e32 v34, v12, v12
	v_mul_f32_e32 v37, v3, v3
	v_mul_f32_e32 v38, v5, v5
	v_fmac_f32_e32 v35, v6, v6
	v_fmac_f32_e32 v36, v8, v8
	v_add_f32_e32 v31, v31, v32
	v_add_f32_e32 v32, v33, v34
	v_fmac_f32_e32 v37, v2, v2
	v_fmac_f32_e32 v38, v4, v4
	v_add_f32_e32 v33, v35, v36
	v_add_f32_e32 v31, v31, v32
	v_add_f32_e32 v34, v37, v38
	v_add_f32_e32 v31, v31, v33
	v_add_f32_e32 v31, v31, v34
	s_nop 1
	v_add_f32_dpp v31, v31, v31 quad_perm:[1,0,3,2] row_mask:0xf bank_mask:0xf
	s_nop 1
	v_add_f32_dpp v31, v31, v31 quad_perm:[2,3,0,1] row_mask:0xf bank_mask:0xf
	s_nop 1
	v_add_f32_dpp v31, v31, v31 row_half_mirror row_mask:0xf bank_mask:0xf
	s_nop 1
	v_add_f32_dpp v31, v31, v31 row_mirror row_mask:0xf bank_mask:0xf
	v_mov_b32_e32 v32, v31
	s_nop 1
	v_permlane16_swap_b32_e32 v32, v31
	v_add_f32_e32 v31, v31, v32
	v_mov_b32_e32 v32, v31
	s_nop 1
	v_permlane32_swap_b32_e32 v32, v31
	v_add_f32_e32 v31, v31, v32
	s_waitcnt lgkmcnt(0)
	s_waitcnt lgkmcnt(0)
	s_waitcnt lgkmcnt(0)
	s_waitcnt lgkmcnt(0)
	s_waitcnt lgkmcnt(0)
	s_waitcnt lgkmcnt(0)
	v_fmamk_f32 v31, v31, 0x3a800000, v18
	v_mul_f32_e32 v32, 0x4f800000, v31
	v_cmp_gt_f32_e32 vcc, s15, v31
	s_nop 1
	v_cndmask_b32_e32 v31, v31, v32, vcc
	v_sqrt_f32_e32 v32, v31
	s_nop 0
	v_add_u32_e32 v33, -1, v32
	v_add_u32_e32 v34, 1, v32
	v_fma_f32 v35, -v33, v32, v31
	v_fma_f32 v36, -v34, v32, v31
	v_cmp_ge_f32_e64 s[4:5], 0, v35
	s_nop 1
	v_cndmask_b32_e64 v32, v32, v33, s[4:5]
	v_cmp_lt_f32_e64 s[4:5], 0, v36
	s_nop 1
	v_cndmask_b32_e64 v32, v32, v34, s[4:5]
	v_mul_f32_e32 v33, 0x37800000, v32
	v_cndmask_b32_e32 v32, v32, v33, vcc
	v_cmp_class_f32_e32 vcc, v31, v30
	s_nop 1
	v_cndmask_b32_e32 v31, v32, v31, vcc
	s_and_saveexec_b64 s[4:5], s[0:1]
	s_cbranch_execz .LBB0_271
	s_lshl_b64 s[18:19], s[10:11], 2
	s_add_u32 s18, s75, s18
	s_addc_u32 s19, s69, s19
	global_store_dword v19, v31, s[18:19]
	s_branch .LBB0_271

.Lrp1_skip:
	v_lshlrev_b32_e32 v50, 16, v34
	v_and_b32_e32 v51, 0xffff0000, v34
	v_alignbit_b32 v34, v35, v34, 16
	v_and_b32_e32 v35, 0xffff0000, v35
	v_lshlrev_b32_e32 v52, 16, v36
	v_and_b32_e32 v53, 0xffff0000, v36
	v_alignbit_b32 v36, v37, v36, 16
	v_and_b32_e32 v37, 0xffff0000, v37
	v_lshlrev_b32_e32 v54, 16, v38
	v_and_b32_e32 v55, 0xffff0000, v38
	v_alignbit_b32 v38, v39, v38, 16
	v_and_b32_e32 v39, 0xffff0000, v39
	v_and_b32_e32 v34, 0xffff0000, v34
	v_and_b32_e32 v36, 0xffff0000, v36
	v_mul_f32_e32 v58, v51, v51
	v_mul_f32_e32 v59, v35, v35
	v_mul_f32_e32 v60, v53, v53
	v_mul_f32_e32 v61, v37, v37
	v_lshlrev_b32_e32 v56, 16, v40
	v_and_b32_e32 v57, 0xffff0000, v40
	v_alignbit_b32 v40, v41, v40, 16
	v_and_b32_e32 v41, 0xffff0000, v41
	v_and_b32_e32 v38, 0xffff0000, v38
	v_mul_f32_e32 v62, v55, v55
	v_mul_f32_e32 v63, v39, v39
	v_fmac_f32_e32 v58, v50, v50
	v_fmac_f32_e32 v59, v34, v34
	v_fmac_f32_e32 v60, v52, v52
	v_fmac_f32_e32 v61, v36, v36
	v_and_b32_e32 v40, 0xffff0000, v40
	v_mul_f32_e32 v64, v57, v57
	v_mul_f32_e32 v65, v41, v41
	v_fmac_f32_e32 v62, v54, v54
	v_fmac_f32_e32 v63, v38, v38
	v_add_f32_e32 v58, v58, v59
	v_add_f32_e32 v59, v60, v61
	v_fmac_f32_e32 v64, v56, v56
	v_fmac_f32_e32 v65, v40, v40
	v_add_f32_e32 v60, v62, v63
	v_add_f32_e32 v58, v58, v59
	v_add_f32_e32 v61, v64, v65
	v_add_f32_e32 v58, v58, v60
	v_add_f32_e32 v60, v58, v61
	s_nop 1
	v_add_f32_dpp v66, v60, v60 quad_perm:[1,0,3,2] row_mask:0xf bank_mask:0xf
	s_nop 1
	v_add_f32_dpp v66, v66, v66 quad_perm:[2,3,0,1] row_mask:0xf bank_mask:0xf
	s_nop 1
	v_add_f32_dpp v66, v66, v66 row_half_mirror row_mask:0xf bank_mask:0xf
	s_nop 1
	v_add_f32_dpp v66, v66, v66 row_mirror row_mask:0xf bank_mask:0xf
	v_mov_b32_e32 v67, v66
	s_nop 1
	v_permlane16_swap_b32_e32 v67, v66
	v_add_f32_e32 v66, v66, v67
	v_mov_b32_e32 v67, v66
	s_nop 1
	v_permlane32_swap_b32_e32 v67, v66
	v_add_f32_e32 v66, v66, v67
	v_lshlrev_b32_e32 v58, 16, v42
	v_and_b32_e32 v59, 0xffff0000, v42
	v_alignbit_b32 v42, v43, v42, 16
	v_pk_mul_f32 v[50:51], v[2:3], v[50:51]
	s_waitcnt lgkmcnt(0)
	v_lshlrev_b32_e32 v60, 16, v44
	v_and_b32_e32 v61, 0xffff0000, v44
	v_alignbit_b32 v44, v45, v44, 16
	v_pk_mul_f32 v[52:53], v[6:7], v[52:53]
	s_waitcnt lgkmcnt(0)
	v_pk_mul_f32 v[34:35], v[4:5], v[34:35]
	v_pk_mul_f32 v[36:37], v[8:9], v[36:37]
	v_and_b32_e32 v43, 0xffff0000, v43
	v_and_b32_e32 v45, 0xffff0000, v45
	s_waitcnt lgkmcnt(0)
	v_and_b32_e32 v42, 0xffff0000, v42
	v_and_b32_e32 v44, 0xffff0000, v44
	v_lshlrev_b32_e32 v62, 16, v46
	v_and_b32_e32 v63, 0xffff0000, v46
	s_waitcnt lgkmcnt(0)
	v_alignbit_b32 v46, v47, v46, 16
	v_pk_mul_f32 v[54:55], v[10:11], v[54:55]
	v_pk_mul_f32 v[38:39], v[12:13], v[38:39]
	v_and_b32_e32 v47, 0xffff0000, v47
	s_waitcnt lgkmcnt(0)
	v_lshlrev_b32_e32 v64, 16, v48
	v_and_b32_e32 v65, 0xffff0000, v48
	v_alignbit_b32 v48, v49, v48, 16
	v_and_b32_e32 v46, 0xffff0000, v46
	s_waitcnt lgkmcnt(0)
	v_fmamk_f32 v66, v66, 0x3a800000, v32
	v_mul_f32_e32 v67, 0x4f800000, v66
	v_cmp_gt_f32_e32 vcc, s17, v66
	v_pk_mul_f32 v[56:57], v[14:15], v[56:57]
	v_pk_mul_f32 v[40:41], v[16:17], v[40:41]
	v_cndmask_b32_e32 v66, v66, v67, vcc
	v_sqrt_f32_e32 v67, v66
	v_and_b32_e32 v49, 0xffff0000, v49
	v_and_b32_e32 v48, 0xffff0000, v48
	v_add_u32_e32 v68, -1, v67
	v_add_u32_e32 v69, 1, v67
	v_fma_f32 v70, -v68, v67, v66
	v_fma_f32 v71, -v69, v67, v66
	v_cmp_ge_f32_e64 s[4:5], 0, v70
	s_nop 1
	v_cndmask_b32_e64 v67, v67, v68, s[4:5]
	v_cmp_lt_f32_e64 s[4:5], 0, v71
	s_nop 1
	v_cndmask_b32_e64 v67, v67, v69, s[4:5]
	v_mul_f32_e32 v68, 0x37800000, v67
	v_cndmask_b32_e32 v67, v67, v68, vcc
	v_cmp_class_f32_e32 vcc, v66, v33
	s_nop 1
	v_cndmask_b32_e32 v66, v67, v66, vcc
	v_div_scale_f32 v67, s[2:3], v66, v66, 0.5
	v_rcp_f32_e32 v68, v67
	v_div_scale_f32 v69, vcc, 0.5, v66, 0.5
	v_fma_f32 v70, -v67, v68, 1.0
	v_fmac_f32_e32 v68, v70, v68
	v_mul_f32_e32 v70, v69, v68
	v_fma_f32 v71, -v67, v70, v69
	v_fmac_f32_e32 v70, v71, v68
	v_fma_f32 v67, -v67, v70, v69
	v_div_fmas_f32 v67, v67, v68, v70
	v_div_fixup_f32 v66, v67, v66, 0.5
	v_pk_mul_f32 v[50:51], v[50:51], v[66:67] op_sel_hi:[1,0]
	v_pk_mul_f32 v[34:35], v[34:35], v[66:67] op_sel_hi:[1,0]
	v_pk_mul_f32 v[52:53], v[52:53], v[66:67] op_sel_hi:[1,0]
	v_pk_mul_f32 v[36:37], v[36:37], v[66:67] op_sel_hi:[1,0]
	v_pk_fma_f32 v[34:35], v[18:19], v[42:43], v[34:35] op_sel_hi:[0,1,1]
	v_pk_fma_f32 v[42:43], v[18:19], v[58:59], v[50:51] op_sel_hi:[0,1,1]
	v_pk_fma_f32 v[36:37], v[18:19], v[44:45], v[36:37] op_sel_hi:[0,1,1]
	v_pk_fma_f32 v[44:45], v[18:19], v[60:61], v[52:53] op_sel_hi:[0,1,1]
	v_pk_mul_f32 v[54:55], v[54:55], v[66:67] op_sel_hi:[1,0]
	v_pk_mul_f32 v[38:39], v[38:39], v[66:67] op_sel_hi:[1,0]
	v_mul_f32_e32 v50, v43, v43
	v_mul_f32_e32 v51, v35, v35
	v_mul_f32_e32 v52, v45, v45
	v_mul_f32_e32 v53, v37, v37
	v_pk_mul_f32 v[56:57], v[56:57], v[66:67] op_sel_hi:[1,0]
	v_pk_fma_f32 v[38:39], v[18:19], v[46:47], v[38:39] op_sel_hi:[0,1,1]
	v_pk_fma_f32 v[46:47], v[18:19], v[62:63], v[54:55] op_sel_hi:[0,1,1]
	v_fmac_f32_e32 v50, v42, v42
	v_fmac_f32_e32 v51, v34, v34
	v_fmac_f32_e32 v52, v44, v44
	v_fmac_f32_e32 v53, v36, v36
	v_pk_mul_f32 v[40:41], v[40:41], v[66:67] op_sel_hi:[1,0]
	v_mul_f32_e32 v54, v47, v47
	v_mul_f32_e32 v55, v39, v39
	v_add_f32_e32 v50, v50, v51
	v_add_f32_e32 v51, v52, v53
	v_pk_fma_f32 v[40:41], v[18:19], v[48:49], v[40:41] op_sel_hi:[0,1,1]
	v_pk_fma_f32 v[48:49], v[18:19], v[64:65], v[56:57] op_sel_hi:[0,1,1]
	v_fmac_f32_e32 v54, v46, v46
	v_fmac_f32_e32 v55, v38, v38
	v_add_f32_e32 v50, v50, v51
	v_mul_f32_e32 v18, v49, v49
	v_mul_f32_e32 v51, v41, v41
	v_add_f32_e32 v52, v54, v55
	v_fmac_f32_e32 v18, v48, v48
	v_fmac_f32_e32 v51, v40, v40
	v_add_f32_e32 v50, v52, v50
	v_add_f32_e32 v18, v18, v51
	v_add_f32_e32 v18, v18, v50
	s_nop 1
	v_add_f32_dpp v18, v18, v18 quad_perm:[1,0,3,2] row_mask:0xf bank_mask:0xf
	s_nop 1
	v_add_f32_dpp v18, v18, v18 quad_perm:[2,3,0,1] row_mask:0xf bank_mask:0xf
	s_nop 1
	v_add_f32_dpp v18, v18, v18 row_half_mirror row_mask:0xf bank_mask:0xf
	s_nop 1
	v_add_f32_dpp v18, v18, v18 row_mirror row_mask:0xf bank_mask:0xf
	v_mov_b32_e32 v50, v18
	s_nop 1
	v_permlane16_swap_b32_e32 v50, v18
	v_add_f32_e32 v18, v18, v50
	v_mov_b32_e32 v50, v18
	s_nop 1
	v_permlane32_swap_b32_e32 v50, v18
	v_add_f32_e32 v18, v18, v50
	s_waitcnt lgkmcnt(0)
	s_waitcnt lgkmcnt(0)
	s_waitcnt lgkmcnt(0)
	s_waitcnt lgkmcnt(0)
	s_waitcnt lgkmcnt(0)
	s_waitcnt lgkmcnt(0)
	v_fmamk_f32 v18, v18, 0x3a800000, v32
	v_mul_f32_e32 v50, 0x4f800000, v18
	v_cmp_gt_f32_e32 vcc, s17, v18
	s_nop 1
	v_cndmask_b32_e32 v18, v18, v50, vcc
	v_sqrt_f32_e32 v50, v18
	s_nop 0
	v_add_u32_e32 v51, -1, v50
	v_add_u32_e32 v52, 1, v50
	v_fma_f32 v53, -v51, v50, v18
	v_fma_f32 v54, -v52, v50, v18
	v_cmp_ge_f32_e64 s[4:5], 0, v53
	s_nop 1
	v_cndmask_b32_e64 v50, v50, v51, s[4:5]
	v_cmp_lt_f32_e64 s[4:5], 0, v54
	s_nop 1
	v_cndmask_b32_e64 v50, v50, v52, s[4:5]
	v_mul_f32_e32 v51, 0x37800000, v50
	v_cndmask_b32_e32 v50, v50, v51, vcc
	v_cmp_class_f32_e32 vcc, v18, v33
	s_nop 1
	v_cndmask_b32_e32 v18, v50, v18, vcc
	v_div_scale_f32 v50, s[2:3], v18, v18, 1.0
	v_rcp_f32_e32 v51, v50
	v_div_scale_f32 v52, vcc, 1.0, v18, 1.0
	v_fma_f32 v53, -v50, v51, 1.0
	v_fmac_f32_e32 v51, v53, v51
	v_mul_f32_e32 v53, v52, v51
	v_fma_f32 v54, -v50, v53, v52
	v_fmac_f32_e32 v53, v54, v51
	v_fma_f32 v50, -v50, v53, v52
	v_div_fmas_f32 v50, v50, v51, v53
	v_div_fixup_f32 v50, v50, v18, 1.0
	v_mul_f32_e32 v42, v42, v50
	v_mul_f32_e32 v34, v34, v50
	v_mul_f32_e32 v43, v43, v50
	v_mul_f32_e32 v35, v35, v50
	v_bfe_u32 v51, v42, 16, 1
	v_bfe_u32 v53, v34, 16, 1
	v_bfe_u32 v52, v43, 16, 1
	v_bfe_u32 v54, v35, 16, 1
	v_add3_u32 v42, v42, v51, s18
	v_add3_u32 v34, v34, v53, s18
	v_add3_u32 v43, v43, v52, s18
	v_add3_u32 v35, v35, v54, s18
	v_lshrrev_b32_e32 v42, 16, v42
	v_lshrrev_b32_e32 v51, 16, v34
	v_mul_f32_e32 v44, v44, v50
	v_and_or_b32 v34, v43, s16, v42
	v_and_or_b32 v35, v35, s16, v51
	global_store_dwordx2 v[24:25], v[34:35], off
	v_mul_f32_e32 v34, v45, v50
	v_bfe_u32 v35, v44, 16, 1
	v_add3_u32 v35, v44, v35, s18
	v_bfe_u32 v42, v34, 16, 1
	v_lshrrev_b32_e32 v35, 16, v35
	v_add3_u32 v34, v34, v42, s18
	v_and_or_b32 v34, v34, s16, v35
	v_mul_f32_e32 v35, v36, v50
	v_mul_f32_e32 v36, v37, v50
	v_bfe_u32 v37, v35, 16, 1
	v_add3_u32 v35, v35, v37, s18
	v_bfe_u32 v37, v36, 16, 1
	v_lshrrev_b32_e32 v35, 16, v35
	v_add3_u32 v36, v36, v37, s18
	v_and_or_b32 v35, v36, s16, v35
	global_store_dwordx2 v[24:25], v[34:35], off offset:512
	v_mul_f32_e32 v34, v46, v50
	v_mul_f32_e32 v35, v47, v50
	v_bfe_u32 v36, v34, 16, 1
	v_add3_u32 v34, v34, v36, s18
	v_bfe_u32 v36, v35, 16, 1
	v_lshrrev_b32_e32 v34, 16, v34
	v_add3_u32 v35, v35, v36, s18
	v_and_or_b32 v34, v35, s16, v34
	v_mul_f32_e32 v35, v38, v50
	v_mul_f32_e32 v36, v39, v50
	v_bfe_u32 v37, v35, 16, 1
	v_add3_u32 v35, v35, v37, s18
	v_bfe_u32 v37, v36, 16, 1
	v_lshrrev_b32_e32 v35, 16, v35
	v_add3_u32 v36, v36, v37, s18
	v_and_or_b32 v35, v36, s16, v35
	global_store_dwordx2 v[24:25], v[34:35], off offset:1024
	v_mul_f32_e32 v34, v48, v50
	v_mul_f32_e32 v35, v49, v50
	v_bfe_u32 v36, v34, 16, 1
	v_add3_u32 v34, v34, v36, s18
	v_bfe_u32 v36, v35, 16, 1
	v_lshrrev_b32_e32 v34, 16, v34
	v_add3_u32 v35, v35, v36, s18
	v_and_or_b32 v34, v35, s16, v34
	v_mul_f32_e32 v35, v40, v50
	v_mul_f32_e32 v36, v41, v50
	v_bfe_u32 v37, v35, 16, 1
	v_add3_u32 v35, v35, v37, s18
	v_bfe_u32 v37, v36, 16, 1
	v_lshrrev_b32_e32 v35, 16, v35
	v_add3_u32 v36, v36, v37, s18
	v_and_or_b32 v35, v36, s16, v35
	global_store_dwordx2 v[24:25], v[34:35], off offset:1536
	s_and_saveexec_b64 s[2:3], s[0:1]
	s_cbranch_execz .LBB0_523
	global_store_dword v19, v18, s[10:11]
	s_branch .LBB0_523

.Lrp2_skip:
	v_and_b32_e32 v51, 0xffff0000, v34
	v_alignbit_b32 v33, v35, v34, 16
	v_and_b32_e32 v35, 0xffff0000, v35
	v_lshlrev_b32_e32 v52, 16, v36
	v_and_b32_e32 v53, 0xffff0000, v36
	v_alignbit_b32 v36, v37, v36, 16
	v_and_b32_e32 v37, 0xffff0000, v37
	v_lshlrev_b32_e32 v50, 16, v34
	v_lshlrev_b32_e32 v54, 16, v38
	v_and_b32_e32 v55, 0xffff0000, v38
	v_alignbit_b32 v38, v39, v38, 16
	v_and_b32_e32 v39, 0xffff0000, v39
	v_and_b32_e32 v34, 0xffff0000, v33
	v_and_b32_e32 v36, 0xffff0000, v36
	v_mul_f32_e32 v33, v51, v51
	v_mul_f32_e32 v58, v35, v35
	v_mul_f32_e32 v59, v53, v53
	v_mul_f32_e32 v60, v37, v37
	v_lshlrev_b32_e32 v56, 16, v40
	v_and_b32_e32 v57, 0xffff0000, v40
	v_alignbit_b32 v40, v41, v40, 16
	v_and_b32_e32 v41, 0xffff0000, v41
	v_and_b32_e32 v38, 0xffff0000, v38
	v_mul_f32_e32 v61, v55, v55
	v_mul_f32_e32 v62, v39, v39
	v_fmac_f32_e32 v33, v50, v50
	v_fmac_f32_e32 v58, v34, v34
	v_fmac_f32_e32 v59, v52, v52
	v_fmac_f32_e32 v60, v36, v36
	v_and_b32_e32 v40, 0xffff0000, v40
	v_mul_f32_e32 v63, v57, v57
	v_mul_f32_e32 v64, v41, v41
	v_fmac_f32_e32 v61, v54, v54
	v_fmac_f32_e32 v62, v38, v38
	v_add_f32_e32 v33, v33, v58
	v_add_f32_e32 v58, v59, v60
	v_fmac_f32_e32 v63, v56, v56
	v_fmac_f32_e32 v64, v40, v40
	v_add_f32_e32 v59, v61, v62
	v_add_f32_e32 v33, v33, v58
	v_add_f32_e32 v60, v63, v64
	v_add_f32_e32 v33, v33, v59
	v_add_f32_e32 v33, v33, v60
	s_nop 1
	v_add_f32_dpp v33, v33, v33 quad_perm:[1,0,3,2] row_mask:0xf bank_mask:0xf
	s_nop 1
	v_add_f32_dpp v33, v33, v33 quad_perm:[2,3,0,1] row_mask:0xf bank_mask:0xf
	s_nop 1
	v_add_f32_dpp v33, v33, v33 row_half_mirror row_mask:0xf bank_mask:0xf
	s_nop 1
	v_add_f32_dpp v33, v33, v33 row_mirror row_mask:0xf bank_mask:0xf
	v_mov_b32_e32 v66, v33
	s_nop 1
	v_permlane16_swap_b32_e32 v66, v33
	v_add_f32_e32 v33, v33, v66
	v_mov_b32_e32 v66, v33
	s_nop 1
	v_permlane32_swap_b32_e32 v66, v33
	v_add_f32_e32 v33, v33, v66
	v_lshlrev_b32_e32 v58, 16, v42
	v_and_b32_e32 v59, 0xffff0000, v42
	v_alignbit_b32 v42, v43, v42, 16
	v_and_b32_e32 v61, 0xffff0000, v44
	s_waitcnt lgkmcnt(0)
	v_lshlrev_b32_e32 v60, 16, v44
	v_alignbit_b32 v44, v45, v44, 16
	v_pk_mul_f32 v[50:51], v[2:3], v[50:51]
	v_pk_mul_f32 v[52:53], v[6:7], v[52:53]
	s_waitcnt lgkmcnt(0)
	v_pk_mul_f32 v[34:35], v[4:5], v[34:35]
	v_pk_mul_f32 v[36:37], v[8:9], v[36:37]
	v_and_b32_e32 v43, 0xffff0000, v43
	v_and_b32_e32 v45, 0xffff0000, v45
	s_waitcnt lgkmcnt(0)
	v_and_b32_e32 v42, 0xffff0000, v42
	v_and_b32_e32 v44, 0xffff0000, v44
	v_lshlrev_b32_e32 v62, 16, v46
	v_and_b32_e32 v63, 0xffff0000, v46
	s_waitcnt lgkmcnt(0)
	v_alignbit_b32 v46, v47, v46, 16
	v_pk_mul_f32 v[54:55], v[10:11], v[54:55]
	v_pk_mul_f32 v[38:39], v[12:13], v[38:39]
	v_and_b32_e32 v47, 0xffff0000, v47
	s_waitcnt lgkmcnt(0)
	v_lshlrev_b32_e32 v64, 16, v48
	v_and_b32_e32 v65, 0xffff0000, v48
	v_alignbit_b32 v48, v49, v48, 16
	v_and_b32_e32 v46, 0xffff0000, v46
	s_waitcnt lgkmcnt(0)
	v_fmamk_f32 v33, v33, 0x3a800000, v31
	v_mul_f32_e32 v66, 0x4f800000, v33
	v_cmp_gt_f32_e32 vcc, s17, v33
	v_pk_mul_f32 v[56:57], v[14:15], v[56:57]
	v_pk_mul_f32 v[40:41], v[16:17], v[40:41]
	v_cndmask_b32_e32 v33, v33, v66, vcc
	v_sqrt_f32_e32 v66, v33
	v_and_b32_e32 v49, 0xffff0000, v49
	v_and_b32_e32 v48, 0xffff0000, v48
	v_add_u32_e32 v67, -1, v66
	v_add_u32_e32 v68, 1, v66
	v_fma_f32 v69, -v67, v66, v33
	v_fma_f32 v70, -v68, v66, v33
	v_cmp_ge_f32_e64 s[4:5], 0, v69
	s_nop 1
	v_cndmask_b32_e64 v66, v66, v67, s[4:5]
	v_cmp_lt_f32_e64 s[4:5], 0, v70
	s_nop 1
	v_cndmask_b32_e64 v66, v66, v68, s[4:5]
	v_mul_f32_e32 v67, 0x37800000, v66
	v_cndmask_b32_e32 v66, v66, v67, vcc
	v_cmp_class_f32_e32 vcc, v33, v32
	s_nop 1
	v_cndmask_b32_e32 v33, v66, v33, vcc
	v_div_scale_f32 v66, s[2:3], v33, v33, 1.0
	v_rcp_f32_e32 v67, v66
	v_div_scale_f32 v68, vcc, 1.0, v33, 1.0
	v_fma_f32 v69, -v66, v67, 1.0
	v_fmac_f32_e32 v67, v69, v67
	v_mul_f32_e32 v69, v68, v67
	v_fma_f32 v70, -v66, v69, v68
	v_fmac_f32_e32 v69, v70, v67
	v_fma_f32 v66, -v66, v69, v68
	v_div_fmas_f32 v66, v66, v67, v69
	v_div_fixup_f32 v66, v66, v33, 1.0
	v_pk_mul_f32 v[50:51], v[50:51], v[66:67] op_sel_hi:[1,0]
	v_pk_mul_f32 v[34:35], v[34:35], v[66:67] op_sel_hi:[1,0]
	v_pk_mul_f32 v[52:53], v[52:53], v[66:67] op_sel_hi:[1,0]
	v_pk_mul_f32 v[36:37], v[36:37], v[66:67] op_sel_hi:[1,0]
	v_pk_fma_f32 v[34:35], v[18:19], v[42:43], v[34:35] op_sel_hi:[0,1,1]
	v_pk_fma_f32 v[42:43], v[18:19], v[58:59], v[50:51] op_sel_hi:[0,1,1]
	v_pk_fma_f32 v[36:37], v[18:19], v[44:45], v[36:37] op_sel_hi:[0,1,1]
	v_pk_fma_f32 v[44:45], v[18:19], v[60:61], v[52:53] op_sel_hi:[0,1,1]
	v_pk_mul_f32 v[54:55], v[54:55], v[66:67] op_sel_hi:[1,0]
	v_pk_mul_f32 v[38:39], v[38:39], v[66:67] op_sel_hi:[1,0]
	v_mul_f32_e32 v33, v43, v43
	v_mul_f32_e32 v50, v35, v35
	v_mul_f32_e32 v51, v45, v45
	v_mul_f32_e32 v52, v37, v37
	v_pk_mul_f32 v[56:57], v[56:57], v[66:67] op_sel_hi:[1,0]
	v_pk_fma_f32 v[38:39], v[18:19], v[46:47], v[38:39] op_sel_hi:[0,1,1]
	v_pk_fma_f32 v[46:47], v[18:19], v[62:63], v[54:55] op_sel_hi:[0,1,1]
	v_fmac_f32_e32 v33, v42, v42
	v_fmac_f32_e32 v50, v34, v34
	v_fmac_f32_e32 v51, v44, v44
	v_fmac_f32_e32 v52, v36, v36
	v_pk_mul_f32 v[40:41], v[40:41], v[66:67] op_sel_hi:[1,0]
	v_mul_f32_e32 v53, v47, v47
	v_mul_f32_e32 v54, v39, v39
	v_add_f32_e32 v33, v33, v50
	v_add_f32_e32 v50, v51, v52
	v_pk_fma_f32 v[40:41], v[18:19], v[48:49], v[40:41] op_sel_hi:[0,1,1]
	v_pk_fma_f32 v[48:49], v[18:19], v[64:65], v[56:57] op_sel_hi:[0,1,1]
	v_fmac_f32_e32 v53, v46, v46
	v_fmac_f32_e32 v54, v38, v38
	v_add_f32_e32 v33, v33, v50
	v_mul_f32_e32 v18, v49, v49
	v_mul_f32_e32 v50, v41, v41
	v_add_f32_e32 v51, v53, v54
	v_fmac_f32_e32 v18, v48, v48
	v_fmac_f32_e32 v50, v40, v40
	v_add_f32_e32 v33, v51, v33
	v_add_f32_e32 v18, v18, v50
	v_add_f32_e32 v18, v18, v33
	s_nop 1
	v_add_f32_dpp v18, v18, v18 quad_perm:[1,0,3,2] row_mask:0xf bank_mask:0xf
	s_nop 1
	v_add_f32_dpp v18, v18, v18 quad_perm:[2,3,0,1] row_mask:0xf bank_mask:0xf
	s_nop 1
	v_add_f32_dpp v18, v18, v18 row_half_mirror row_mask:0xf bank_mask:0xf
	s_nop 1
	v_add_f32_dpp v18, v18, v18 row_mirror row_mask:0xf bank_mask:0xf
	v_mov_b32_e32 v33, v18
	s_nop 1
	v_permlane16_swap_b32_e32 v33, v18
	v_add_f32_e32 v18, v18, v33
	v_mov_b32_e32 v33, v18
	s_nop 1
	v_permlane32_swap_b32_e32 v33, v18
	v_add_f32_e32 v18, v18, v33
	s_waitcnt lgkmcnt(0)
	s_waitcnt lgkmcnt(0)
	s_waitcnt lgkmcnt(0)
	s_waitcnt lgkmcnt(0)
	s_waitcnt lgkmcnt(0)
	s_waitcnt lgkmcnt(0)
	v_fmamk_f32 v18, v18, 0x3a800000, v31
	v_mul_f32_e32 v33, 0x4f800000, v18
	v_cmp_gt_f32_e32 vcc, s17, v18
	s_nop 1
	v_cndmask_b32_e32 v18, v18, v33, vcc
	v_sqrt_f32_e32 v33, v18
	s_nop 0
	v_add_u32_e32 v50, -1, v33
	v_add_u32_e32 v51, 1, v33
	v_fma_f32 v52, -v50, v33, v18
	v_fma_f32 v53, -v51, v33, v18
	v_cmp_ge_f32_e64 s[4:5], 0, v52
	s_nop 1
	v_cndmask_b32_e64 v33, v33, v50, s[4:5]
	v_cmp_lt_f32_e64 s[4:5], 0, v53
	s_nop 1
	v_cndmask_b32_e64 v33, v33, v51, s[4:5]
	v_mul_f32_e32 v50, 0x37800000, v33
	v_cndmask_b32_e32 v33, v33, v50, vcc
	v_cmp_class_f32_e32 vcc, v18, v32
	s_nop 1
	v_cndmask_b32_e32 v18, v33, v18, vcc
	v_div_scale_f32 v33, s[2:3], v18, v18, 1.0
	v_rcp_f32_e32 v50, v33
	v_div_scale_f32 v51, vcc, 1.0, v18, 1.0
	v_fma_f32 v52, -v33, v50, 1.0
	v_fmac_f32_e32 v50, v52, v50
	v_mul_f32_e32 v52, v51, v50
	v_fma_f32 v53, -v33, v52, v51
	v_fmac_f32_e32 v52, v53, v50
	v_fma_f32 v33, -v33, v52, v51
	v_div_fmas_f32 v33, v33, v50, v52
	v_div_fixup_f32 v33, v33, v18, 1.0
	v_mul_f32_e32 v42, v42, v33
	v_mul_f32_e32 v34, v34, v33
	v_mul_f32_e32 v43, v43, v33
	v_mul_f32_e32 v35, v35, v33
	v_bfe_u32 v50, v42, 16, 1
	v_bfe_u32 v52, v34, 16, 1
	v_bfe_u32 v51, v43, 16, 1
	v_bfe_u32 v53, v35, 16, 1
	v_add3_u32 v42, v42, v50, s18
	v_add3_u32 v34, v34, v52, s18
	v_add3_u32 v43, v43, v51, s18
	v_add3_u32 v35, v35, v53, s18
	v_lshrrev_b32_e32 v42, 16, v42
	v_lshrrev_b32_e32 v50, 16, v34
	v_mul_f32_e32 v44, v44, v33
	v_and_or_b32 v34, v43, s16, v42
	v_and_or_b32 v35, v35, s16, v50
	global_store_dwordx2 v[24:25], v[34:35], off
	v_mul_f32_e32 v34, v45, v33
	v_bfe_u32 v35, v44, 16, 1
	v_add3_u32 v35, v44, v35, s18
	v_bfe_u32 v42, v34, 16, 1
	v_lshrrev_b32_e32 v35, 16, v35
	v_add3_u32 v34, v34, v42, s18
	v_and_or_b32 v34, v34, s16, v35
	v_mul_f32_e32 v35, v36, v33
	v_mul_f32_e32 v36, v37, v33
	v_bfe_u32 v37, v35, 16, 1
	v_add3_u32 v35, v35, v37, s18
	v_bfe_u32 v37, v36, 16, 1
	v_lshrrev_b32_e32 v35, 16, v35
	v_add3_u32 v36, v36, v37, s18
	v_and_or_b32 v35, v36, s16, v35
	global_store_dwordx2 v[24:25], v[34:35], off offset:512
	v_mul_f32_e32 v34, v46, v33
	v_mul_f32_e32 v35, v47, v33
	v_bfe_u32 v36, v34, 16, 1
	v_add3_u32 v34, v34, v36, s18
	v_bfe_u32 v36, v35, 16, 1
	v_lshrrev_b32_e32 v34, 16, v34
	v_add3_u32 v35, v35, v36, s18
	v_and_or_b32 v34, v35, s16, v34
	v_mul_f32_e32 v35, v38, v33
	v_mul_f32_e32 v36, v39, v33
	v_bfe_u32 v37, v35, 16, 1
	v_add3_u32 v35, v35, v37, s18
	v_bfe_u32 v37, v36, 16, 1
	v_lshrrev_b32_e32 v35, 16, v35
	v_add3_u32 v36, v36, v37, s18
	v_and_or_b32 v35, v36, s16, v35
	global_store_dwordx2 v[24:25], v[34:35], off offset:1024
	v_mul_f32_e32 v34, v48, v33
	v_mul_f32_e32 v35, v49, v33
	v_bfe_u32 v36, v34, 16, 1
	v_add3_u32 v34, v34, v36, s18
	v_bfe_u32 v36, v35, 16, 1
	v_lshrrev_b32_e32 v34, 16, v34
	v_add3_u32 v35, v35, v36, s18
	v_and_or_b32 v34, v35, s16, v34
	v_mul_f32_e32 v35, v40, v33
	v_mul_f32_e32 v33, v41, v33
	v_bfe_u32 v36, v35, 16, 1
	v_add3_u32 v35, v35, v36, s18
	v_bfe_u32 v36, v33, 16, 1
	v_lshrrev_b32_e32 v35, 16, v35
	v_add3_u32 v33, v33, v36, s18
	v_and_or_b32 v35, v33, s16, v35
	global_store_dwordx2 v[24:25], v[34:35], off offset:1536
	s_and_saveexec_b64 s[2:3], s[0:1]
	s_cbranch_execz .LBB0_1126
	global_store_dword v19, v18, s[10:11]
	s_branch .LBB0_1126

.Lrp3_skip:
	v_and_b32_e32 v51, 0xffff0000, v34
	v_alignbit_b32 v33, v35, v34, 16
	v_and_b32_e32 v35, 0xffff0000, v35
	v_lshlrev_b32_e32 v52, 16, v36
	v_and_b32_e32 v53, 0xffff0000, v36
	v_alignbit_b32 v36, v37, v36, 16
	v_and_b32_e32 v37, 0xffff0000, v37
	v_lshlrev_b32_e32 v50, 16, v34
	v_lshlrev_b32_e32 v54, 16, v38
	v_and_b32_e32 v55, 0xffff0000, v38
	v_alignbit_b32 v38, v39, v38, 16
	v_and_b32_e32 v39, 0xffff0000, v39
	v_and_b32_e32 v34, 0xffff0000, v33
	v_and_b32_e32 v36, 0xffff0000, v36
	v_mul_f32_e32 v33, v51, v51
	v_mul_f32_e32 v58, v35, v35
	v_mul_f32_e32 v59, v53, v53
	v_mul_f32_e32 v60, v37, v37
	v_lshlrev_b32_e32 v56, 16, v40
	v_and_b32_e32 v57, 0xffff0000, v40
	v_alignbit_b32 v40, v41, v40, 16
	v_and_b32_e32 v41, 0xffff0000, v41
	v_and_b32_e32 v38, 0xffff0000, v38
	v_mul_f32_e32 v61, v55, v55
	v_mul_f32_e32 v62, v39, v39
	v_fmac_f32_e32 v33, v50, v50
	v_fmac_f32_e32 v58, v34, v34
	v_fmac_f32_e32 v59, v52, v52
	v_fmac_f32_e32 v60, v36, v36
	v_and_b32_e32 v40, 0xffff0000, v40
	v_mul_f32_e32 v63, v57, v57
	v_mul_f32_e32 v64, v41, v41
	v_fmac_f32_e32 v61, v54, v54
	v_fmac_f32_e32 v62, v38, v38
	v_add_f32_e32 v33, v33, v58
	v_add_f32_e32 v58, v59, v60
	v_fmac_f32_e32 v63, v56, v56
	v_fmac_f32_e32 v64, v40, v40
	v_add_f32_e32 v59, v61, v62
	v_add_f32_e32 v33, v33, v58
	v_add_f32_e32 v60, v63, v64
	v_add_f32_e32 v33, v33, v59
	v_add_f32_e32 v33, v33, v60
	s_nop 1
	v_add_f32_dpp v33, v33, v33 quad_perm:[1,0,3,2] row_mask:0xf bank_mask:0xf
	s_nop 1
	v_add_f32_dpp v33, v33, v33 quad_perm:[2,3,0,1] row_mask:0xf bank_mask:0xf
	s_nop 1
	v_add_f32_dpp v33, v33, v33 row_half_mirror row_mask:0xf bank_mask:0xf
	s_nop 1
	v_add_f32_dpp v33, v33, v33 row_mirror row_mask:0xf bank_mask:0xf
	v_mov_b32_e32 v66, v33
	s_nop 1
	v_permlane16_swap_b32_e32 v66, v33
	v_add_f32_e32 v33, v33, v66
	v_mov_b32_e32 v66, v33
	s_nop 1
	v_permlane32_swap_b32_e32 v66, v33
	v_add_f32_e32 v33, v33, v66
	v_lshlrev_b32_e32 v58, 16, v42
	v_and_b32_e32 v59, 0xffff0000, v42
	v_alignbit_b32 v42, v43, v42, 16
	v_and_b32_e32 v61, 0xffff0000, v44
	s_waitcnt lgkmcnt(0)
	v_lshlrev_b32_e32 v60, 16, v44
	v_alignbit_b32 v44, v45, v44, 16
	v_pk_mul_f32 v[50:51], v[2:3], v[50:51]
	v_pk_mul_f32 v[52:53], v[6:7], v[52:53]
	s_waitcnt lgkmcnt(0)
	v_pk_mul_f32 v[34:35], v[4:5], v[34:35]
	v_pk_mul_f32 v[36:37], v[8:9], v[36:37]
	v_and_b32_e32 v43, 0xffff0000, v43
	v_and_b32_e32 v45, 0xffff0000, v45
	s_waitcnt lgkmcnt(0)
	v_and_b32_e32 v42, 0xffff0000, v42
	v_and_b32_e32 v44, 0xffff0000, v44
	v_lshlrev_b32_e32 v62, 16, v46
	v_and_b32_e32 v63, 0xffff0000, v46
	s_waitcnt lgkmcnt(0)
	v_alignbit_b32 v46, v47, v46, 16
	v_pk_mul_f32 v[54:55], v[10:11], v[54:55]
	v_pk_mul_f32 v[38:39], v[12:13], v[38:39]
	v_and_b32_e32 v47, 0xffff0000, v47
	s_waitcnt lgkmcnt(0)
	v_lshlrev_b32_e32 v64, 16, v48
	v_and_b32_e32 v65, 0xffff0000, v48
	v_alignbit_b32 v48, v49, v48, 16
	v_and_b32_e32 v46, 0xffff0000, v46
	s_waitcnt lgkmcnt(0)
	v_fmamk_f32 v33, v33, 0x3a800000, v31
	v_mul_f32_e32 v66, 0x4f800000, v33
	v_cmp_gt_f32_e32 vcc, s18, v33
	v_pk_mul_f32 v[56:57], v[14:15], v[56:57]
	v_pk_mul_f32 v[40:41], v[16:17], v[40:41]
	v_cndmask_b32_e32 v33, v33, v66, vcc
	v_sqrt_f32_e32 v66, v33
	v_and_b32_e32 v49, 0xffff0000, v49
	v_and_b32_e32 v48, 0xffff0000, v48
	v_add_u32_e32 v67, -1, v66
	v_add_u32_e32 v68, 1, v66
	v_fma_f32 v69, -v67, v66, v33
	v_fma_f32 v70, -v68, v66, v33
	v_cmp_ge_f32_e64 s[4:5], 0, v69
	s_nop 1
	v_cndmask_b32_e64 v66, v66, v67, s[4:5]
	v_cmp_lt_f32_e64 s[4:5], 0, v70
	s_nop 1
	v_cndmask_b32_e64 v66, v66, v68, s[4:5]
	v_mul_f32_e32 v67, 0x37800000, v66
	v_cndmask_b32_e32 v66, v66, v67, vcc
	v_cmp_class_f32_e32 vcc, v33, v32
	s_nop 1
	v_cndmask_b32_e32 v33, v66, v33, vcc
	v_div_scale_f32 v66, s[2:3], v33, v33, 1.0
	v_rcp_f32_e32 v67, v66
	v_div_scale_f32 v68, vcc, 1.0, v33, 1.0
	v_fma_f32 v69, -v66, v67, 1.0
	v_fmac_f32_e32 v67, v69, v67
	v_mul_f32_e32 v69, v68, v67
	v_fma_f32 v70, -v66, v69, v68
	v_fmac_f32_e32 v69, v70, v67
	v_fma_f32 v66, -v66, v69, v68
	v_div_fmas_f32 v66, v66, v67, v69
	v_div_fixup_f32 v66, v66, v33, 1.0
	v_pk_mul_f32 v[50:51], v[50:51], v[66:67] op_sel_hi:[1,0]
	v_pk_mul_f32 v[34:35], v[34:35], v[66:67] op_sel_hi:[1,0]
	v_pk_mul_f32 v[52:53], v[52:53], v[66:67] op_sel_hi:[1,0]
	v_pk_mul_f32 v[36:37], v[36:37], v[66:67] op_sel_hi:[1,0]
	v_pk_fma_f32 v[34:35], v[18:19], v[42:43], v[34:35] op_sel_hi:[0,1,1]
	v_pk_fma_f32 v[42:43], v[18:19], v[58:59], v[50:51] op_sel_hi:[0,1,1]
	v_pk_fma_f32 v[36:37], v[18:19], v[44:45], v[36:37] op_sel_hi:[0,1,1]
	v_pk_fma_f32 v[44:45], v[18:19], v[60:61], v[52:53] op_sel_hi:[0,1,1]
	v_pk_mul_f32 v[54:55], v[54:55], v[66:67] op_sel_hi:[1,0]
	v_pk_mul_f32 v[38:39], v[38:39], v[66:67] op_sel_hi:[1,0]
	v_mul_f32_e32 v33, v43, v43
	v_mul_f32_e32 v50, v35, v35
	v_mul_f32_e32 v51, v45, v45
	v_mul_f32_e32 v52, v37, v37
	v_pk_mul_f32 v[56:57], v[56:57], v[66:67] op_sel_hi:[1,0]
	v_pk_fma_f32 v[38:39], v[18:19], v[46:47], v[38:39] op_sel_hi:[0,1,1]
	v_pk_fma_f32 v[46:47], v[18:19], v[62:63], v[54:55] op_sel_hi:[0,1,1]
	v_fmac_f32_e32 v33, v42, v42
	v_fmac_f32_e32 v50, v34, v34
	v_fmac_f32_e32 v51, v44, v44
	v_fmac_f32_e32 v52, v36, v36
	v_pk_mul_f32 v[40:41], v[40:41], v[66:67] op_sel_hi:[1,0]
	v_mul_f32_e32 v53, v47, v47
	v_mul_f32_e32 v54, v39, v39
	v_add_f32_e32 v33, v33, v50
	v_add_f32_e32 v50, v51, v52
	v_pk_fma_f32 v[40:41], v[18:19], v[48:49], v[40:41] op_sel_hi:[0,1,1]
	v_pk_fma_f32 v[48:49], v[18:19], v[64:65], v[56:57] op_sel_hi:[0,1,1]
	v_fmac_f32_e32 v53, v46, v46
	v_fmac_f32_e32 v54, v38, v38
	v_add_f32_e32 v33, v33, v50
	v_mul_f32_e32 v18, v49, v49
	v_mul_f32_e32 v50, v41, v41
	v_add_f32_e32 v51, v53, v54
	v_fmac_f32_e32 v18, v48, v48
	v_fmac_f32_e32 v50, v40, v40
	v_add_f32_e32 v33, v51, v33
	v_add_f32_e32 v18, v18, v50
	v_add_f32_e32 v18, v18, v33
	s_nop 1
	v_add_f32_dpp v18, v18, v18 quad_perm:[1,0,3,2] row_mask:0xf bank_mask:0xf
	s_nop 1
	v_add_f32_dpp v18, v18, v18 quad_perm:[2,3,0,1] row_mask:0xf bank_mask:0xf
	s_nop 1
	v_add_f32_dpp v18, v18, v18 row_half_mirror row_mask:0xf bank_mask:0xf
	s_nop 1
	v_add_f32_dpp v18, v18, v18 row_mirror row_mask:0xf bank_mask:0xf
	v_mov_b32_e32 v33, v18
	s_nop 1
	v_permlane16_swap_b32_e32 v33, v18
	v_add_f32_e32 v18, v18, v33
	v_mov_b32_e32 v33, v18
	s_nop 1
	v_permlane32_swap_b32_e32 v33, v18
	v_add_f32_e32 v18, v18, v33
	s_waitcnt lgkmcnt(0)
	s_waitcnt lgkmcnt(0)
	s_waitcnt lgkmcnt(0)
	s_waitcnt lgkmcnt(0)
	s_waitcnt lgkmcnt(0)
	s_waitcnt lgkmcnt(0)
	v_fmamk_f32 v18, v18, 0x3a800000, v31
	v_mul_f32_e32 v33, 0x4f800000, v18
	v_cmp_gt_f32_e32 vcc, s18, v18
	s_nop 1
	v_cndmask_b32_e32 v18, v18, v33, vcc
	v_sqrt_f32_e32 v33, v18
	s_nop 0
	v_add_u32_e32 v50, -1, v33
	v_add_u32_e32 v51, 1, v33
	v_fma_f32 v52, -v50, v33, v18
	v_fma_f32 v53, -v51, v33, v18
	v_cmp_ge_f32_e64 s[4:5], 0, v52
	s_nop 1
	v_cndmask_b32_e64 v33, v33, v50, s[4:5]
	v_cmp_lt_f32_e64 s[4:5], 0, v53
	s_nop 1
	v_cndmask_b32_e64 v33, v33, v51, s[4:5]
	v_mul_f32_e32 v50, 0x37800000, v33
	v_cndmask_b32_e32 v33, v33, v50, vcc
	v_cmp_class_f32_e32 vcc, v18, v32
	s_nop 1
	v_cndmask_b32_e32 v18, v33, v18, vcc
	v_div_scale_f32 v33, s[2:3], v18, v18, 1.0
	v_rcp_f32_e32 v50, v33
	v_div_scale_f32 v51, vcc, 1.0, v18, 1.0
	v_fma_f32 v52, -v33, v50, 1.0
	v_fmac_f32_e32 v50, v52, v50
	v_mul_f32_e32 v52, v51, v50
	v_fma_f32 v53, -v33, v52, v51
	v_fmac_f32_e32 v52, v53, v50
	v_fma_f32 v33, -v33, v52, v51
	v_div_fmas_f32 v33, v33, v50, v52
	v_div_fixup_f32 v33, v33, v18, 1.0
	v_mul_f32_e32 v42, v42, v33
	v_mul_f32_e32 v34, v34, v33
	v_mul_f32_e32 v43, v43, v33
	v_mul_f32_e32 v35, v35, v33
	v_bfe_u32 v50, v42, 16, 1
	v_bfe_u32 v52, v34, 16, 1
	v_bfe_u32 v51, v43, 16, 1
	v_bfe_u32 v53, v35, 16, 1
	v_add3_u32 v42, v42, v50, s19
	v_add3_u32 v34, v34, v52, s19
	v_add3_u32 v43, v43, v51, s19
	v_add3_u32 v35, v35, v53, s19
	v_lshrrev_b32_e32 v42, 16, v42
	v_lshrrev_b32_e32 v50, 16, v34
	v_mul_f32_e32 v44, v44, v33
	v_and_or_b32 v34, v43, s17, v42
	v_and_or_b32 v35, v35, s17, v50
	global_store_dwordx2 v[24:25], v[34:35], off
	v_mul_f32_e32 v34, v45, v33
	v_bfe_u32 v35, v44, 16, 1
	v_add3_u32 v35, v44, v35, s19
	v_bfe_u32 v42, v34, 16, 1
	v_lshrrev_b32_e32 v35, 16, v35
	v_add3_u32 v34, v34, v42, s19
	v_and_or_b32 v34, v34, s17, v35
	v_mul_f32_e32 v35, v36, v33
	v_mul_f32_e32 v36, v37, v33
	v_bfe_u32 v37, v35, 16, 1
	v_add3_u32 v35, v35, v37, s19
	v_bfe_u32 v37, v36, 16, 1
	v_lshrrev_b32_e32 v35, 16, v35
	v_add3_u32 v36, v36, v37, s19
	v_and_or_b32 v35, v36, s17, v35
	global_store_dwordx2 v[24:25], v[34:35], off offset:512
	v_mul_f32_e32 v34, v46, v33
	v_mul_f32_e32 v35, v47, v33
	v_bfe_u32 v36, v34, 16, 1
	v_add3_u32 v34, v34, v36, s19
	v_bfe_u32 v36, v35, 16, 1
	v_lshrrev_b32_e32 v34, 16, v34
	v_add3_u32 v35, v35, v36, s19
	v_and_or_b32 v34, v35, s17, v34
	v_mul_f32_e32 v35, v38, v33
	v_mul_f32_e32 v36, v39, v33
	v_bfe_u32 v37, v35, 16, 1
	v_add3_u32 v35, v35, v37, s19
	v_bfe_u32 v37, v36, 16, 1
	v_lshrrev_b32_e32 v35, 16, v35
	v_add3_u32 v36, v36, v37, s19
	v_and_or_b32 v35, v36, s17, v35
	global_store_dwordx2 v[24:25], v[34:35], off offset:1024
	v_mul_f32_e32 v34, v48, v33
	v_mul_f32_e32 v35, v49, v33
	v_bfe_u32 v36, v34, 16, 1
	v_add3_u32 v34, v34, v36, s19
	v_bfe_u32 v36, v35, 16, 1
	v_lshrrev_b32_e32 v34, 16, v34
	v_add3_u32 v35, v35, v36, s19
	v_and_or_b32 v34, v35, s17, v34
	v_mul_f32_e32 v35, v40, v33
	v_mul_f32_e32 v33, v41, v33
	v_bfe_u32 v36, v35, 16, 1
	v_add3_u32 v35, v35, v36, s19
	v_bfe_u32 v36, v33, 16, 1
	v_lshrrev_b32_e32 v35, 16, v35
	v_add3_u32 v33, v33, v36, s19
	v_and_or_b32 v35, v33, s17, v35
	global_store_dwordx2 v[24:25], v[34:35], off offset:1536
	s_and_saveexec_b64 s[2:3], s[0:1]
	s_cbranch_execz .LBB0_1267
	global_store_dword v19, v18, s[10:11]
	s_branch .LBB0_1267

.Lrp4_skip:
	v_lshlrev_b32_e32 v66, 16, v42
	v_and_b32_e32 v67, 0xffff0000, v42
	v_alignbit_b32 v42, v43, v42, 16
	v_and_b32_e32 v43, 0xffff0000, v43
	v_lshlrev_b32_e32 v68, 16, v44
	v_and_b32_e32 v69, 0xffff0000, v44
	v_alignbit_b32 v44, v45, v44, 16
	v_and_b32_e32 v45, 0xffff0000, v45
	v_lshlrev_b32_e32 v70, 16, v46
	v_and_b32_e32 v71, 0xffff0000, v46
	v_alignbit_b32 v46, v47, v46, 16
	v_and_b32_e32 v47, 0xffff0000, v47
	v_and_b32_e32 v42, 0xffff0000, v42
	v_and_b32_e32 v44, 0xffff0000, v44
	v_mul_f32_e32 v74, v67, v67
	v_mul_f32_e32 v75, v43, v43
	v_mul_f32_e32 v76, v69, v69
	v_mul_f32_e32 v77, v45, v45
	v_lshlrev_b32_e32 v72, 16, v48
	v_and_b32_e32 v73, 0xffff0000, v48
	v_alignbit_b32 v48, v49, v48, 16
	v_and_b32_e32 v49, 0xffff0000, v49
	v_and_b32_e32 v46, 0xffff0000, v46
	v_mul_f32_e32 v78, v71, v71
	v_mul_f32_e32 v79, v47, v47
	v_fmac_f32_e32 v74, v66, v66
	v_fmac_f32_e32 v75, v42, v42
	v_fmac_f32_e32 v76, v68, v68
	v_fmac_f32_e32 v77, v44, v44
	v_and_b32_e32 v48, 0xffff0000, v48
	v_mul_f32_e32 v80, v73, v73
	v_mul_f32_e32 v81, v49, v49
	v_fmac_f32_e32 v78, v70, v70
	v_fmac_f32_e32 v79, v46, v46
	v_add_f32_e32 v74, v74, v75
	v_add_f32_e32 v75, v76, v77
	v_fmac_f32_e32 v80, v72, v72
	v_fmac_f32_e32 v81, v48, v48
	v_add_f32_e32 v76, v78, v79
	v_add_f32_e32 v74, v74, v75
	v_add_f32_e32 v77, v80, v81
	v_add_f32_e32 v74, v74, v76
	v_add_f32_e32 v76, v74, v77
	s_nop 1
	v_add_f32_dpp v86, v76, v76 quad_perm:[1,0,3,2] row_mask:0xf bank_mask:0xf
	s_nop 1
	v_add_f32_dpp v86, v86, v86 quad_perm:[2,3,0,1] row_mask:0xf bank_mask:0xf
	s_nop 1
	v_add_f32_dpp v86, v86, v86 row_half_mirror row_mask:0xf bank_mask:0xf
	s_nop 1
	v_add_f32_dpp v86, v86, v86 row_mirror row_mask:0xf bank_mask:0xf
	v_mov_b32_e32 v87, v86
	s_nop 1
	v_permlane16_swap_b32_e32 v87, v86
	v_add_f32_e32 v86, v86, v87
	v_mov_b32_e32 v87, v86
	s_nop 1
	v_permlane32_swap_b32_e32 v87, v86
	v_add_f32_e32 v86, v86, v87
	v_and_b32_e32 v81, 0xffff0000, v55
	v_and_b32_e32 v83, 0xffff0000, v56
	v_and_b32_e32 v85, 0xffff0000, v57
	v_lshlrev_b32_e32 v74, 16, v50
	s_waitcnt lgkmcnt(0)
	v_and_b32_e32 v75, 0xffff0000, v50
	v_alignbit_b32 v50, v51, v50, 16
	v_lshlrev_b32_e32 v76, 16, v52
	v_and_b32_e32 v77, 0xffff0000, v52
	s_waitcnt lgkmcnt(0)
	v_lshlrev_b32_e32 v78, 16, v54
	v_and_b32_e32 v79, 0xffff0000, v54
	v_alignbit_b32 v54, v55, v54, 16
	v_alignbit_b32 v52, v53, v52, 16
	s_waitcnt lgkmcnt(0)
	v_lshlrev_b32_e32 v82, 16, v56
	v_alignbit_b32 v56, v57, v56, 16
	v_and_b32_e32 v84, 0xffff0000, v56
	v_pk_mul_f32 v[42:43], v[2:3], v[42:43]
	s_waitcnt lgkmcnt(0)
	v_and_b32_e32 v80, 0xffff0000, v54
	v_pk_mul_f32 v[44:45], v[14:15], v[44:45]
	v_and_b32_e32 v51, 0xffff0000, v51
	v_and_b32_e32 v53, 0xffff0000, v53
	s_waitcnt lgkmcnt(0)
	v_pk_mul_f32 v[54:55], v[0:1], v[66:67]
	v_pk_mul_f32 v[66:67], v[16:17], v[70:71]
	v_pk_mul_f32 v[56:57], v[12:13], v[68:69]
	v_pk_mul_f32 v[68:69], v[28:29], v[72:73]
	s_waitcnt lgkmcnt(0)
	v_mov_b32_e32 v70, v86
	v_fmamk_f32 v70, v70, 0x3a800000, v64
	v_mul_f32_e32 v71, 0x4f800000, v70
	v_cmp_gt_f32_e32 vcc, s17, v70
	v_and_b32_e32 v50, 0xffff0000, v50
	v_and_b32_e32 v52, 0xffff0000, v52
	v_cndmask_b32_e32 v70, v70, v71, vcc
	v_sqrt_f32_e32 v71, v70
	v_pk_mul_f32 v[46:47], v[18:19], v[46:47]
	v_pk_mul_f32 v[48:49], v[30:31], v[48:49]
	v_add_u32_e32 v72, -1, v71
	v_add_u32_e32 v73, 1, v71
	v_fma_f32 v86, -v72, v71, v70
	v_fma_f32 v87, -v73, v71, v70
	v_cmp_ge_f32_e64 s[2:3], 0, v86
	s_nop 1
	v_cndmask_b32_e64 v71, v71, v72, s[2:3]
	v_cmp_lt_f32_e64 s[2:3], 0, v87
	s_nop 1
	v_cndmask_b32_e64 v71, v71, v73, s[2:3]
	v_mul_f32_e32 v72, 0x37800000, v71
	v_cndmask_b32_e32 v71, v71, v72, vcc
	v_cmp_class_f32_e32 vcc, v70, v65
	s_nop 1
	v_cndmask_b32_e32 v70, v71, v70, vcc
	v_div_scale_f32 v71, s[2:3], v70, v70, 0.5
	v_rcp_f32_e32 v72, v71
	v_div_scale_f32 v73, vcc, 0.5, v70, 0.5
	v_fma_f32 v86, -v71, v72, 1.0
	v_fmac_f32_e32 v72, v86, v72
	v_mul_f32_e32 v86, v73, v72
	v_fma_f32 v87, -v71, v86, v73
	v_fmac_f32_e32 v86, v87, v72
	v_fma_f32 v71, -v71, v86, v73
	v_div_fmas_f32 v71, v71, v72, v86
	v_div_fixup_f32 v70, v71, v70, 0.5
	v_pk_mul_f32 v[72:73], v[54:55], v[70:71] op_sel_hi:[1,0]
	v_pk_mul_f32 v[42:43], v[42:43], v[70:71] op_sel_hi:[1,0]
	v_pk_mul_f32 v[86:87], v[56:57], v[70:71] op_sel_hi:[1,0]
	v_pk_mul_f32 v[44:45], v[44:45], v[70:71] op_sel_hi:[1,0]
	v_pk_mul_f32 v[66:67], v[66:67], v[70:71] op_sel_hi:[1,0]
	v_pk_mul_f32 v[46:47], v[46:47], v[70:71] op_sel_hi:[1,0]
	v_pk_fma_f32 v[54:55], v[32:33], v[50:51], v[42:43] op_sel_hi:[0,1,1]
	v_pk_fma_f32 v[56:57], v[32:33], v[74:75], v[72:73] op_sel_hi:[0,1,1]
	v_pk_fma_f32 v[50:51], v[32:33], v[52:53], v[44:45] op_sel_hi:[0,1,1]
	v_pk_fma_f32 v[52:53], v[32:33], v[76:77], v[86:87] op_sel_hi:[0,1,1]
	v_pk_fma_f32 v[42:43], v[32:33], v[80:81], v[46:47] op_sel_hi:[0,1,1]
	v_pk_fma_f32 v[46:47], v[32:33], v[78:79], v[66:67] op_sel_hi:[0,1,1]
	v_mul_f32_e32 v44, v57, v57
	v_mul_f32_e32 v45, v55, v55
	v_mul_f32_e32 v66, v53, v53
	v_mul_f32_e32 v67, v51, v51
	v_pk_mul_f32 v[68:69], v[68:69], v[70:71] op_sel_hi:[1,0]
	v_mul_f32_e32 v71, v47, v47
	v_mul_f32_e32 v72, v43, v43
	v_fmac_f32_e32 v44, v56, v56
	v_fmac_f32_e32 v45, v54, v54
	v_fmac_f32_e32 v66, v52, v52
	v_fmac_f32_e32 v67, v50, v50
	v_fmac_f32_e32 v71, v46, v46
	v_fmac_f32_e32 v72, v42, v42
	v_add_f32_e32 v44, v44, v45
	v_add_f32_e32 v45, v66, v67
	v_add_f32_e32 v66, v71, v72
	v_add_f32_e32 v44, v44, v45
	v_add_f32_e32 v66, v66, v44
	v_pk_mul_f32 v[44:45], v[48:49], v[70:71] op_sel_hi:[1,0]
	v_pk_fma_f32 v[48:49], v[32:33], v[82:83], v[68:69] op_sel_hi:[0,1,1]
	v_pk_fma_f32 v[44:45], v[32:33], v[84:85], v[44:45] op_sel_hi:[0,1,1]
	v_mul_f32_e32 v32, v49, v49
	v_mul_f32_e32 v67, v45, v45
	v_fmac_f32_e32 v32, v48, v48
	v_fmac_f32_e32 v67, v44, v44
	v_add_f32_e32 v32, v32, v67
	v_add_f32_e32 v32, v32, v66
	s_nop 1
	v_add_f32_dpp v32, v32, v32 quad_perm:[1,0,3,2] row_mask:0xf bank_mask:0xf
	s_nop 1
	v_add_f32_dpp v32, v32, v32 quad_perm:[2,3,0,1] row_mask:0xf bank_mask:0xf
	s_nop 1
	v_add_f32_dpp v32, v32, v32 row_half_mirror row_mask:0xf bank_mask:0xf
	s_nop 1
	v_add_f32_dpp v32, v32, v32 row_mirror row_mask:0xf bank_mask:0xf
	v_mov_b32_e32 v66, v32
	s_nop 1
	v_permlane16_swap_b32_e32 v66, v32
	v_add_f32_e32 v32, v32, v66
	v_mov_b32_e32 v66, v32
	s_nop 1
	v_permlane32_swap_b32_e32 v66, v32
	v_add_f32_e32 v32, v32, v66
	s_waitcnt lgkmcnt(0)
	s_waitcnt lgkmcnt(0)
	s_waitcnt lgkmcnt(0)
	s_waitcnt lgkmcnt(0)
	s_waitcnt lgkmcnt(0)
	s_waitcnt lgkmcnt(0)
	v_fmamk_f32 v32, v32, 0x3a800000, v64
	v_mul_f32_e32 v66, 0x4f800000, v32
	v_cmp_gt_f32_e32 vcc, s17, v32
	s_nop 1
	v_cndmask_b32_e32 v32, v32, v66, vcc
	v_sqrt_f32_e32 v66, v32
	s_nop 0
	v_add_u32_e32 v67, -1, v66
	v_add_u32_e32 v68, 1, v66
	v_fma_f32 v69, -v67, v66, v32
	v_fma_f32 v70, -v68, v66, v32
	v_cmp_ge_f32_e64 s[2:3], 0, v69
	s_nop 1
	v_cndmask_b32_e64 v66, v66, v67, s[2:3]
	v_cmp_lt_f32_e64 s[2:3], 0, v70
	s_nop 1
	v_cndmask_b32_e64 v66, v66, v68, s[2:3]
	v_mul_f32_e32 v67, 0x37800000, v66
	v_cndmask_b32_e32 v66, v66, v67, vcc
	v_cmp_class_f32_e32 vcc, v32, v65
	s_nop 1
	v_cndmask_b32_e32 v66, v66, v32, vcc
	v_div_scale_f32 v32, s[2:3], v66, v66, 1.0
	v_rcp_f32_e32 v67, v32
	v_div_scale_f32 v68, vcc, 1.0, v66, 1.0
	s_and_b64 s[2:3], exec, s[4:5]
	v_fma_f32 v69, -v32, v67, 1.0
	v_fmac_f32_e32 v67, v69, v67
	v_mul_f32_e32 v69, v68, v67
	v_fma_f32 v70, -v32, v69, v68
	v_fmac_f32_e32 v69, v70, v67
	v_fma_f32 v32, -v32, v69, v68
	v_div_fmas_f32 v32, v32, v67, v69
	v_div_fixup_f32 v32, v32, v66, 1.0
	s_mov_b64 vcc, s[2:3]
	s_cbranch_vccz .LBB0_1484
	s_lshl_b64 s[2:3], s[10:11], 10
	v_pk_mul_f32 v[70:71], v[10:11], v[54:55]
	v_pk_mul_f32 v[68:69], v[8:9], v[56:57]
	v_lshl_add_u64 v[72:73], s[2:3], 2, v[38:39]
	v_pk_mul_f32 v[68:69], v[68:69], v[32:33] op_sel_hi:[1,0]
	v_pk_mul_f32 v[70:71], v[70:71], v[32:33] op_sel_hi:[1,0]
	global_store_dwordx4 v[72:73], v[68:71], off
	s_nop 1
	v_pk_mul_f32 v[70:71], v[6:7], v[50:51]
	v_pk_mul_f32 v[68:69], v[4:5], v[52:53]
	v_pk_mul_f32 v[70:71], v[70:71], v[32:33] op_sel_hi:[1,0]
	v_pk_mul_f32 v[68:69], v[68:69], v[32:33] op_sel_hi:[1,0]
	global_store_dwordx4 v[72:73], v[68:71], off offset:1024
	s_nop 1
	v_pk_mul_f32 v[70:71], v[26:27], v[42:43]
	v_pk_mul_f32 v[68:69], v[24:25], v[46:47]
	v_pk_mul_f32 v[70:71], v[70:71], v[32:33] op_sel_hi:[1,0]
	v_pk_mul_f32 v[68:69], v[68:69], v[32:33] op_sel_hi:[1,0]
	global_store_dwordx4 v[72:73], v[68:71], off offset:2048
	s_nop 1
	v_pk_mul_f32 v[70:71], v[22:23], v[44:45]
	v_pk_mul_f32 v[68:69], v[20:21], v[48:49]
	v_pk_mul_f32 v[70:71], v[70:71], v[32:33] op_sel_hi:[1,0]
	v_pk_mul_f32 v[68:69], v[68:69], v[32:33] op_sel_hi:[1,0]
	global_store_dwordx4 v[72:73], v[68:71], off offset:3072
	s_cbranch_execnz .LBB0_1481
	s_branch .LBB0_1485
